# speedup vs baseline: 1.0274x; 1.0058x over previous
; #define p getp()
; template <int MODE>
; __device__ __forceinline__ void rms_rows(KP p, const float* __restrict__ g, int wv) {
;     ...
;   for (int row = blockIdx.x * 8 + wid; row < TOK; row += gridDim.x * 8) {
;     const float* src;
;     if (MODE == 0) src = (row < SEQ) ? p->x_prompt + (long)row * DM : p->x_sample + (long)(row - SEQ) * DM;
;     else src = p->X + (long)row * DM;
;     f32x4 v[8];
; #pragma unroll
;     for (int i = 0; i < 8; ++i) v[i] = *reinterpret_cast<const f32x4*>(src + (i * 64 + lane) * 4);
;     float ss = 0.f;
; #pragma unroll
;     for (int i = 0; i < 8; ++i) ss += v[i][0] * v[i][0] + v[i][1] * v[i][1] + v[i][2] * v[i][2] + v[i][3] * v[i][3];
;     ss = wave_sum(ss);
;     const float rstd = rsqrtf(ss * (1.f / DM) + 1e-6f);
.LBB0_69:
	v_cmp_gt_i32_e32 vcc, s1, v74
	v_add_u32_e32 v6, 0xffffc000, v74
	v_ashrrev_i32_e32 v7, 31, v74
	v_cndmask_b32_e64 v34, 8, 0, vcc
	v_lshl_add_u64 v[8:9], s[14:15], 0, v[34:35]
	global_load_dwordx2 v[8:9], v[8:9], off
	v_cndmask_b32_e32 v7, 0, v7, vcc
	v_cndmask_b32_e32 v6, v6, v74, vcc
	v_lshlrev_b64 v[6:7], 13, v[6:7]
	v_mov_b32_e32 v65, v35
	v_mov_b32_e32 v67, v35
	v_mov_b32_e32 v69, v35
	v_mov_b32_e32 v71, v35
	v_mov_b32_e32 v73, v35
	s_waitcnt vmcnt(0)
	v_lshl_add_u64 v[6:7], v[8:9], 0, v[6:7]
	v_lshl_add_u64 v[88:89], v[6:7], 0, v[48:49]
	v_lshl_add_u64 v[90:91], v[6:7], 0, v[50:51]
	v_lshl_add_u64 v[92:93], v[6:7], 0, v[52:53]
	v_lshl_add_u64 v[94:95], v[6:7], 0, v[54:55]
	v_lshl_add_u64 v[96:97], v[6:7], 0, v[46:47]
	global_load_dwordx4 v[18:21], v[88:89], off nt
	global_load_dwordx4 v[14:17], v[90:91], off nt
	global_load_dwordx4 v[10:13], v[92:93], off nt
	global_load_dwordx4 v[6:9], v[94:95], off nt
	global_load_dwordx4 v[84:87], v[96:97], off nt
	global_load_dwordx4 v[30:33], v[96:97], off offset:1024 nt
	global_load_dwordx4 v[26:29], v[96:97], off offset:2048 nt
	global_load_dwordx4 v[22:25], v[96:97], off offset:3072 nt
	s_waitcnt vmcnt(7)
	v_mov_b32_e32 v90, v19
	s_waitcnt vmcnt(6)
	v_mov_b32_e32 v91, v15
	v_mov_b32_e32 v88, v18
	v_mov_b32_e32 v89, v14
	s_waitcnt vmcnt(3)
	v_mul_f32_e32 v34, v85, v85
	s_waitcnt vmcnt(2)
	v_mul_f32_e32 v57, v31, v31
	s_waitcnt vmcnt(1)
	v_mul_f32_e32 v59, v27, v27
	v_fmac_f32_e32 v34, v84, v84
	v_fmac_f32_e32 v57, v30, v30
	s_waitcnt vmcnt(0)
	v_mul_f32_e32 v61, v23, v23
	v_fmac_f32_e32 v59, v26, v26
	v_fmac_f32_e32 v34, v86, v86
	v_fmac_f32_e32 v57, v32, v32
	v_pk_mul_f32 v[90:91], v[90:91], v[90:91]
	v_fmac_f32_e32 v61, v22, v22
	v_fmac_f32_e32 v59, v28, v28
	v_fmac_f32_e32 v34, v87, v87
	v_fmac_f32_e32 v57, v33, v33
	v_mov_b32_e32 v94, v11
	v_mov_b32_e32 v95, v7
	v_mov_b32_e32 v96, v20
	v_mov_b32_e32 v97, v16
	v_pk_fma_f32 v[88:89], v[88:89], v[88:89], v[90:91]
	v_fmac_f32_e32 v61, v24, v24
	v_fmac_f32_e32 v59, v29, v29
	v_add_f32_e32 v34, v34, v57
	v_mov_b32_e32 v92, v10
	v_mov_b32_e32 v93, v6
	v_mov_b32_e32 v100, v21
	v_mov_b32_e32 v101, v17
	v_pk_mul_f32 v[94:95], v[94:95], v[94:95]
	v_pk_fma_f32 v[88:89], v[96:97], v[96:97], v[88:89]
	v_fmac_f32_e32 v61, v25, v25
	v_add_f32_e32 v34, v34, v59
	v_mov_b32_e32 v98, v12
	v_mov_b32_e32 v99, v8
	v_pk_fma_f32 v[90:91], v[92:93], v[92:93], v[94:95]
	v_pk_fma_f32 v[88:89], v[100:101], v[100:101], v[88:89]
	v_add_f32_e32 v34, v34, v61
	v_mov_b32_e32 v102, v13
	v_mov_b32_e32 v103, v9
	v_pk_fma_f32 v[90:91], v[98:99], v[98:99], v[90:91]
	v_add_f32_e32 v34, v34, v88
	v_pk_fma_f32 v[90:91], v[102:103], v[102:103], v[90:91]
	v_add_f32_e32 v34, v34, v89
	v_add_f32_e32 v34, v34, v90
	v_add_f32_e32 v34, v34, v91
	ds_bpermute_b32 v57, v75, v34
	v_ashrrev_i32_e32 v90, 8, v74
	v_ashrrev_i32_e32 v91, 31, v90
	v_lshlrev_b64 v[90:91], 20, v[90:91]
	v_add_u32_e32 v74, s0, v74
	s_waitcnt lgkmcnt(0)
	v_add_f32_e32 v34, v34, v57
	ds_bpermute_b32 v57, v76, v34
	s_waitcnt lgkmcnt(0)
	v_add_f32_e32 v34, v34, v57
	ds_bpermute_b32 v57, v77, v34
	s_waitcnt lgkmcnt(0)
	v_add_f32_e32 v34, v34, v57
	ds_bpermute_b32 v57, v78, v34
	s_waitcnt lgkmcnt(0)
	v_add_f32_e32 v34, v34, v57
	ds_bpermute_b32 v57, v79, v34
	s_waitcnt lgkmcnt(0)
	v_add_f32_e32 v34, v34, v57
	ds_bpermute_b32 v57, v80, v34
	s_waitcnt lgkmcnt(0)
	v_add_f32_e32 v34, v34, v57
	v_fmamk_f32 v34, v34, 0x3a000000, v82
	v_mul_f32_e32 v57, 0x4b800000, v34
	v_cmp_gt_f32_e32 vcc, s3, v34
	s_nop 1
	v_cndmask_b32_e32 v34, v34, v57, vcc
	v_rsq_f32_e32 v34, v34
	s_nop 0
	v_mul_f32_e32 v57, 0x45800000, v34
	v_cndmask_b32_e32 v83, v34, v57, vcc
	v_mul_f32_e32 v34, v84, v83
	v_mul_f32_e32 v57, v85, v83
	v_mul_f32_e32 v59, v86, v83
	v_mul_f32_e32 v61, v87, v83
	v_mul_f32_e32 v34, v2, v34
	v_mul_f32_e32 v57, v3, v57
	v_mul_f32_e32 v59, v4, v59
	v_mul_f32_e32 v61, v5, v61
	v_cvt_pk_bf16_f32 v88, v34, v57
	v_cvt_pk_bf16_f32 v89, v59, v61
	s_load_dwordx2 s[16:17], s[14:15], 0xa8
	v_mul_f32_e32 v61, v30, v83
	v_mul_f32_e32 v63, v31, v83
	v_and_b32_e32 v34, 0x3fc0, v81
	v_mov_b32_e32 v57, v35
	s_waitcnt lgkmcnt(0)
; __device__ __forceinline__ long ablk(int row, int col, int nkt) { return ((long)(row >> 8) * nkt + (col >> 6)) * 16384 + (row & 255) * 64 + (col & 63); }
; #define p getp()
; template <int MODE>
; __device__ __forceinline__ void rms_rows(KP p, const float* __restrict__ g, int wv) {
;     ...
; #pragma unroll
;     for (int i = 0; i < 8; ++i) {
;       const int c = (i * 64 + lane) * 4;
;       f32x4 gg = *reinterpret_cast<const f32x4*>(g + c);
;       f32x4 y = {v[i][0] * rstd * gg[0], v[i][1] * rstd * gg[1], v[i][2] * rstd * gg[2], v[i][3] * rstd * gg[3]};
;       if (MODE == 2) *reinterpret_cast<f32x4*>(p->X + (long)row * DM + c) = y;
;       else { u32x2 w = {cvtpk(y[0], y[1]), cvtpk(y[2], y[3])}; *reinterpret_cast<u32x2*>(P_H + ablk(row, c, DM / 64)) = w; }
;     }
	v_lshl_add_u64 v[30:31], s[16:17], 0, v[90:91]
	v_lshl_add_u64 v[90:91], v[30:31], 0, s[8:9]
	v_lshlrev_b32_e32 v34, 1, v34
	v_lshl_add_u64 v[30:31], v[90:91], 0, v[56:57]
	v_mov_b32_e32 v59, v35
	v_lshl_add_u64 v[30:31], v[30:31], 0, v[34:35]
	v_mul_f32_e32 v32, v32, v83
	v_mul_f32_e32 v33, v33, v83
	v_lshl_add_u64 v[30:31], v[30:31], 0, v[58:59]
	global_store_dwordx2 v[30:31], v[88:89], off
	v_mul_f32_e32 v57, v26, v83
	v_mul_f32_e32 v28, v28, v83
	v_mul_f32_e32 v29, v29, v83
	v_mul_f32_e32 v24, v24, v83
	v_mul_f32_e32 v25, v25, v83
	v_mul_f32_e32 v20, v20, v83
	v_mul_f32_e32 v21, v21, v83
	v_mul_f32_e32 v16, v16, v83
	v_mul_f32_e32 v17, v17, v83
	v_mul_f32_e32 v12, v12, v83
	v_mul_f32_e32 v13, v13, v83
	v_cmp_lt_i32_e32 vcc, s10, v74
	v_add_u32_e32 v81, s38, v81
	s_or_b64 s[6:7], vcc, s[6:7]
	v_mul_f32_e32 v30, v144, v61
	v_mul_f32_e32 v31, v145, v63
	v_mul_f32_e32 v32, v146, v32
	v_mul_f32_e32 v33, v147, v33
	v_cvt_pk_bf16_f32 v84, v30, v31
	v_cvt_pk_bf16_f32 v85, v32, v33
	v_mov_b32_e32 v61, v35
	v_mul_f32_e32 v63, v27, v83
	v_lshl_add_u64 v[26:27], v[90:91], 0, v[60:61]
	v_lshl_add_u64 v[26:27], v[26:27], 0, v[34:35]
	v_lshl_add_u64 v[26:27], v[26:27], 0, v[58:59]
	global_store_dwordx2 v[26:27], v[84:85], off
	v_mul_f32_e32 v26, v148, v57
	v_mul_f32_e32 v27, v149, v63
	v_mul_f32_e32 v28, v150, v28
	v_mul_f32_e32 v29, v151, v29
	v_cvt_pk_bf16_f32 v30, v26, v27
	v_cvt_pk_bf16_f32 v31, v28, v29
	v_mov_b32_e32 v63, v35
	v_mul_f32_e32 v32, v22, v83
	v_mul_f32_e32 v33, v23, v83
	v_lshl_add_u64 v[22:23], v[90:91], 0, v[62:63]
	v_lshl_add_u64 v[22:23], v[22:23], 0, v[34:35]
	v_lshl_add_u64 v[22:23], v[22:23], 0, v[58:59]
	global_store_dwordx2 v[22:23], v[30:31], off
	v_mul_f32_e32 v22, v32, v152
	v_mul_f32_e32 v23, v33, v153
	v_mul_f32_e32 v24, v24, v154
	v_mul_f32_e32 v25, v25, v155
	v_cvt_pk_bf16_f32 v26, v22, v23
	v_cvt_pk_bf16_f32 v27, v24, v25
	v_mul_f32_e32 v28, v18, v83
	v_mul_f32_e32 v29, v19, v83
	v_lshl_add_u64 v[18:19], v[90:91], 0, v[64:65]
	v_lshl_add_u64 v[18:19], v[18:19], 0, v[34:35]
	v_lshl_add_u64 v[18:19], v[18:19], 0, v[58:59]
	global_store_dwordx2 v[18:19], v[26:27], off
	v_mul_f32_e32 v18, v28, v156
	v_mul_f32_e32 v19, v29, v157
	v_mul_f32_e32 v20, v20, v158
	v_mul_f32_e32 v21, v21, v159
	v_cvt_pk_bf16_f32 v22, v18, v19
	v_cvt_pk_bf16_f32 v23, v20, v21
	v_mul_f32_e32 v24, v14, v83
	v_mul_f32_e32 v25, v15, v83
	v_lshl_add_u64 v[14:15], v[90:91], 0, v[66:67]
	v_lshl_add_u64 v[14:15], v[14:15], 0, v[34:35]
	v_lshl_add_u64 v[14:15], v[14:15], 0, v[58:59]
	global_store_dwordx2 v[14:15], v[22:23], off
	v_mul_f32_e32 v14, v24, v160
	v_mul_f32_e32 v15, v25, v161
	v_mul_f32_e32 v16, v16, v162
	v_mul_f32_e32 v17, v17, v163
	v_cvt_pk_bf16_f32 v18, v14, v15
	v_cvt_pk_bf16_f32 v19, v16, v17
	v_mul_f32_e32 v20, v10, v83
	v_mul_f32_e32 v21, v11, v83
	v_lshl_add_u64 v[10:11], v[90:91], 0, v[68:69]
	v_lshl_add_u64 v[10:11], v[10:11], 0, v[34:35]
	v_lshl_add_u64 v[10:11], v[10:11], 0, v[58:59]
	global_store_dwordx2 v[10:11], v[18:19], off
	v_mul_f32_e32 v18, v8, v83
	v_mul_f32_e32 v19, v9, v83
	v_lshl_add_u64 v[8:9], v[90:91], 0, v[72:73]
	v_lshl_add_u64 v[8:9], v[8:9], 0, v[34:35]
	v_lshl_add_u64 v[8:9], v[8:9], 0, v[58:59]
	v_mul_f32_e32 v10, v20, v164
	v_mul_f32_e32 v11, v21, v165
	v_mul_f32_e32 v12, v12, v166
	v_mul_f32_e32 v13, v13, v167
	v_cvt_pk_bf16_f32 v14, v10, v11
	v_cvt_pk_bf16_f32 v15, v12, v13
	v_mul_f32_e32 v16, v6, v83
	v_mul_f32_e32 v17, v7, v83
	v_lshl_add_u64 v[6:7], v[90:91], 0, v[70:71]
	v_lshl_add_u64 v[6:7], v[6:7], 0, v[34:35]
	v_lshl_add_u64 v[6:7], v[6:7], 0, v[58:59]
	global_store_dwordx2 v[6:7], v[14:15], off
	v_mul_f32_e32 v6, v16, v168
	v_mul_f32_e32 v7, v17, v169
	v_mul_f32_e32 v10, v18, v170
	v_mul_f32_e32 v11, v19, v171
	v_cvt_pk_bf16_f32 v6, v6, v7
	v_cvt_pk_bf16_f32 v7, v10, v11
	global_store_dwordx2 v[8:9], v[6:7], off
	s_andn2_b64 exec, exec, s[6:7]
	s_cbranch_execnz .LBB0_69

; #define p getp()
; template <int MODE>
; __device__ __forceinline__ void rms_rows(KP p, const float* __restrict__ g, int wv) {
;     ...
;   for (int row = blockIdx.x * 8 + wid; row < TOK; row += gridDim.x * 8) {
;     const float* src;
;     if (MODE == 0) src = (row < SEQ) ? p->x_prompt + (long)row * DM : p->x_sample + (long)(row - SEQ) * DM;
;     else src = p->X + (long)row * DM;
;     f32x4 v[8];
; #pragma unroll
;     for (int i = 0; i < 8; ++i) v[i] = *reinterpret_cast<const f32x4*>(src + (i * 64 + lane) * 4);
;     float ss = 0.f;
; #pragma unroll
;     for (int i = 0; i < 8; ++i) ss += v[i][0] * v[i][0] + v[i][1] * v[i][1] + v[i][2] * v[i][2] + v[i][3] * v[i][3];
;     ss = wave_sum(ss);
;     const float rstd = rsqrtf(ss * (1.f / DM) + 1e-6f);
.LBB0_541:
	v_ashrrev_i32_e32 v21, 31, v20
	v_lshlrev_b64 v[4:5], 13, v[20:21]
	v_lshl_add_u64 v[4:5], s[10:11], 0, v[4:5]
	v_lshl_add_u64 v[84:85], v[4:5], 0, v[34:35]
	v_lshl_add_u64 v[86:87], v[4:5], 0, v[36:37]
	v_lshl_add_u64 v[88:89], v[4:5], 0, v[38:39]
	v_lshl_add_u64 v[90:91], v[4:5], 0, v[40:41]
	v_lshl_add_u64 v[92:93], v[4:5], 0, v[42:43]
	global_load_dwordx4 v[68:71], v[84:85], off nt
	global_load_dwordx4 v[72:75], v[84:85], off offset:1024 nt
	global_load_dwordx4 v[76:79], v[84:85], off offset:2048 nt
	global_load_dwordx4 v[80:83], v[84:85], off offset:3072 nt
	global_load_dwordx4 v[16:19], v[86:87], off nt
	global_load_dwordx4 v[12:15], v[88:89], off nt
	global_load_dwordx4 v[8:11], v[90:91], off nt
	global_load_dwordx4 v[4:7], v[92:93], off nt
	v_mov_b32_e32 v57, v23
	v_mov_b32_e32 v59, v23
	s_waitcnt vmcnt(7)
	v_mul_f32_e32 v21, v69, v69
	s_waitcnt vmcnt(6)
	v_mul_f32_e32 v45, v73, v73
	s_waitcnt vmcnt(5)
	v_mul_f32_e32 v47, v77, v77
	v_fmac_f32_e32 v21, v68, v68
	v_fmac_f32_e32 v45, v72, v72
	s_waitcnt vmcnt(4)
	v_mul_f32_e32 v49, v81, v81
	s_waitcnt vmcnt(3)
	v_mov_b32_e32 v86, v17
	s_waitcnt vmcnt(2)
	v_mov_b32_e32 v87, v13
	v_fmac_f32_e32 v47, v76, v76
	v_fmac_f32_e32 v21, v70, v70
	v_fmac_f32_e32 v45, v74, v74
	v_mov_b32_e32 v84, v16
	v_mov_b32_e32 v85, v12
	v_fmac_f32_e32 v49, v80, v80
	v_pk_mul_f32 v[86:87], v[86:87], v[86:87]
	v_fmac_f32_e32 v47, v78, v78
	v_fmac_f32_e32 v21, v71, v71
	v_fmac_f32_e32 v45, v75, v75
	v_mov_b32_e32 v88, v18
	v_mov_b32_e32 v89, v14
	s_waitcnt vmcnt(1)
	v_mov_b32_e32 v94, v9
	s_waitcnt vmcnt(0)
	v_mov_b32_e32 v95, v5
	v_fmac_f32_e32 v49, v82, v82
	v_pk_fma_f32 v[84:85], v[84:85], v[84:85], v[86:87]
	v_fmac_f32_e32 v47, v79, v79
	v_add_f32_e32 v21, v21, v45
	v_mov_b32_e32 v90, v19
	v_mov_b32_e32 v91, v15
	v_mov_b32_e32 v92, v8
	v_mov_b32_e32 v93, v4
	v_pk_mul_f32 v[94:95], v[94:95], v[94:95]
	v_fmac_f32_e32 v49, v83, v83
	v_pk_fma_f32 v[84:85], v[88:89], v[88:89], v[84:85]
	v_add_f32_e32 v21, v21, v47
	v_mov_b32_e32 v96, v10
	v_mov_b32_e32 v97, v6
	v_pk_fma_f32 v[86:87], v[92:93], v[92:93], v[94:95]
	v_pk_fma_f32 v[84:85], v[90:91], v[90:91], v[84:85]
	v_add_f32_e32 v21, v21, v49
	v_mov_b32_e32 v98, v11
	v_mov_b32_e32 v99, v7
	v_pk_fma_f32 v[86:87], v[96:97], v[96:97], v[86:87]
	v_add_f32_e32 v21, v21, v84
	v_pk_fma_f32 v[86:87], v[98:99], v[98:99], v[86:87]
	v_add_f32_e32 v21, v21, v85
	v_add_f32_e32 v21, v21, v86
	v_add_f32_e32 v21, v21, v87
	ds_bpermute_b32 v45, v60, v21
	v_ashrrev_i32_e32 v86, 8, v20
	v_ashrrev_i32_e32 v87, 31, v86
	v_lshlrev_b64 v[86:87], 20, v[86:87]
	v_mov_b32_e32 v89, v23
	s_waitcnt lgkmcnt(0)
	v_add_f32_e32 v21, v21, v45
	ds_bpermute_b32 v45, v61, v21
	v_add_u32_e32 v20, s0, v20
	s_waitcnt lgkmcnt(0)
	v_add_f32_e32 v21, v21, v45
	ds_bpermute_b32 v45, v62, v21
	s_waitcnt lgkmcnt(0)
	v_add_f32_e32 v21, v21, v45
	ds_bpermute_b32 v45, v63, v21
	s_waitcnt lgkmcnt(0)
	v_add_f32_e32 v21, v21, v45
	ds_bpermute_b32 v45, v64, v21
	s_waitcnt lgkmcnt(0)
	v_add_f32_e32 v21, v21, v45
	ds_bpermute_b32 v45, v65, v21
	s_waitcnt lgkmcnt(0)
	v_add_f32_e32 v21, v21, v45
	v_fmamk_f32 v21, v21, 0x3a000000, v67
	v_mul_f32_e32 v45, 0x4b800000, v21
	v_cmp_gt_f32_e32 vcc, s1, v21
	s_nop 1
	v_cndmask_b32_e32 v21, v21, v45, vcc
	v_rsq_f32_e32 v21, v21
	s_nop 0
	v_mul_f32_e32 v45, 0x45800000, v21
	v_cndmask_b32_e32 v21, v21, v45, vcc
	v_mul_f32_e32 v45, v68, v21
	v_mul_f32_e32 v47, v69, v21
	v_mul_f32_e32 v49, v70, v21
	v_mul_f32_e32 v51, v71, v21
	v_mul_f32_e32 v45, v0, v45
	v_mul_f32_e32 v47, v1, v47
	v_mul_f32_e32 v49, v2, v49
	v_mul_f32_e32 v51, v3, v51
	v_cvt_pk_bf16_f32 v84, v45, v47
	v_cvt_pk_bf16_f32 v85, v49, v51
	s_load_dwordx2 s[16:17], s[4:5], 0xa8
	v_and_b32_e32 v47, 0x3fc0, v66
	v_lshlrev_b32_e32 v88, 1, v47
	v_mul_f32_e32 v47, v72, v21
	v_mul_f32_e32 v49, v73, v21
	s_waitcnt lgkmcnt(0)
; __device__ __forceinline__ long ablk(int row, int col, int nkt) { return ((long)(row >> 8) * nkt + (col >> 6)) * 16384 + (row & 255) * 64 + (col & 63); }
; #define p getp()
; template <int MODE>
; __device__ __forceinline__ void rms_rows(KP p, const float* __restrict__ g, int wv) {
;     ...
; #pragma unroll
;     for (int i = 0; i < 8; ++i) {
;       const int c = (i * 64 + lane) * 4;
;       f32x4 gg = *reinterpret_cast<const f32x4*>(g + c);
;       f32x4 y = {v[i][0] * rstd * gg[0], v[i][1] * rstd * gg[1], v[i][2] * rstd * gg[2], v[i][3] * rstd * gg[3]};
;       if (MODE == 2) *reinterpret_cast<f32x4*>(p->X + (long)row * DM + c) = y;
;       else { u32x2 w = {cvtpk(y[0], y[1]), cvtpk(y[2], y[3])}; *reinterpret_cast<u32x2*>(P_H + ablk(row, c, DM / 64)) = w; }
;     }
	v_lshl_add_u64 v[72:73], s[16:17], 0, v[86:87]
	v_lshl_add_u64 v[72:73], v[72:73], 0, s[14:15]
	v_mul_f32_e32 v51, v74, v21
	v_mul_f32_e32 v53, v75, v21
	v_lshl_add_u64 v[74:75], v[72:73], 0, v[22:23]
	v_mov_b32_e32 v45, v23
	v_lshl_add_u64 v[74:75], v[74:75], 0, v[88:89]
	v_lshl_add_u64 v[74:75], v[74:75], 0, v[44:45]
	global_store_dwordx2 v[74:75], v[84:85], off
	v_mul_f32_e32 v55, v79, v21
	v_mul_f32_e32 v18, v18, v21
	v_mul_f32_e32 v19, v19, v21
	v_mul_f32_e32 v14, v14, v21
	v_mul_f32_e32 v15, v15, v21
	v_mul_f32_e32 v10, v10, v21
	v_mul_f32_e32 v11, v11, v21
	v_cmp_lt_i32_e32 vcc, s3, v20
	v_add_u32_e32 v66, s38, v66
	s_or_b64 s[12:13], vcc, s[12:13]
	v_mul_f32_e32 v47, v144, v47
	v_mul_f32_e32 v49, v145, v49
	v_mul_f32_e32 v51, v146, v51
	v_mul_f32_e32 v53, v147, v53
	v_cvt_pk_bf16_f32 v74, v47, v49
	v_cvt_pk_bf16_f32 v75, v51, v53
	v_mov_b32_e32 v47, v23
	v_mul_f32_e32 v49, v76, v21
	v_mul_f32_e32 v51, v77, v21
	v_lshl_add_u64 v[76:77], v[72:73], 0, v[46:47]
	v_lshl_add_u64 v[76:77], v[76:77], 0, v[88:89]
	v_mul_f32_e32 v53, v78, v21
	v_lshl_add_u64 v[76:77], v[76:77], 0, v[44:45]
	global_store_dwordx2 v[76:77], v[74:75], off
	v_mul_f32_e32 v47, v148, v49
	v_mul_f32_e32 v49, v149, v51
	v_mul_f32_e32 v51, v150, v53
	v_mul_f32_e32 v53, v151, v55
	v_cvt_pk_bf16_f32 v74, v47, v49
	v_cvt_pk_bf16_f32 v75, v51, v53
	v_mov_b32_e32 v49, v23
	v_lshl_add_u64 v[76:77], v[72:73], 0, v[48:49]
	v_lshl_add_u64 v[76:77], v[76:77], 0, v[88:89]
	v_mul_f32_e32 v47, v80, v21
	v_mul_f32_e32 v51, v81, v21
	v_mul_f32_e32 v53, v82, v21
	v_mul_f32_e32 v55, v83, v21
	v_lshl_add_u64 v[76:77], v[76:77], 0, v[44:45]
	global_store_dwordx2 v[76:77], v[74:75], off
	v_mul_f32_e32 v47, v47, v152
	v_mul_f32_e32 v49, v51, v153
	v_mul_f32_e32 v51, v53, v154
	v_mul_f32_e32 v53, v55, v155
	v_cvt_pk_bf16_f32 v74, v47, v49
	v_cvt_pk_bf16_f32 v75, v51, v53
	v_mov_b32_e32 v51, v23
	v_mul_f32_e32 v47, v16, v21
	v_mul_f32_e32 v49, v17, v21
	v_lshl_add_u64 v[16:17], v[72:73], 0, v[50:51]
	v_lshl_add_u64 v[16:17], v[16:17], 0, v[88:89]
	v_lshl_add_u64 v[16:17], v[16:17], 0, v[44:45]
	global_store_dwordx2 v[16:17], v[74:75], off
	v_mov_b32_e32 v53, v23
	v_mov_b32_e32 v55, v23
	v_mul_f32_e32 v16, v47, v156
	v_mul_f32_e32 v17, v49, v157
	v_mul_f32_e32 v18, v18, v158
	v_mul_f32_e32 v19, v19, v159
	v_cvt_pk_bf16_f32 v68, v16, v17
	v_cvt_pk_bf16_f32 v69, v18, v19
	v_mul_f32_e32 v47, v12, v21
	v_mul_f32_e32 v49, v13, v21
	v_lshl_add_u64 v[12:13], v[72:73], 0, v[52:53]
	v_lshl_add_u64 v[12:13], v[12:13], 0, v[88:89]
	v_lshl_add_u64 v[12:13], v[12:13], 0, v[44:45]
	global_store_dwordx2 v[12:13], v[68:69], off
	v_mul_f32_e32 v12, v47, v160
	v_mul_f32_e32 v13, v49, v161
	v_mul_f32_e32 v14, v14, v162
	v_mul_f32_e32 v15, v15, v163
	v_cvt_pk_bf16_f32 v16, v12, v13
	v_cvt_pk_bf16_f32 v17, v14, v15
	v_mul_f32_e32 v18, v8, v21
	v_mul_f32_e32 v19, v9, v21
	v_lshl_add_u64 v[8:9], v[72:73], 0, v[54:55]
	v_lshl_add_u64 v[8:9], v[8:9], 0, v[88:89]
	v_lshl_add_u64 v[8:9], v[8:9], 0, v[44:45]
	global_store_dwordx2 v[8:9], v[16:17], off
	v_mul_f32_e32 v16, v6, v21
	v_mul_f32_e32 v17, v7, v21
	v_lshl_add_u64 v[6:7], v[72:73], 0, v[58:59]
	v_lshl_add_u64 v[6:7], v[6:7], 0, v[88:89]
	v_lshl_add_u64 v[6:7], v[6:7], 0, v[44:45]
	v_mul_f32_e32 v8, v18, v164
	v_mul_f32_e32 v9, v19, v165
	v_mul_f32_e32 v10, v10, v166
	v_mul_f32_e32 v11, v11, v167
	v_cvt_pk_bf16_f32 v12, v8, v9
	v_cvt_pk_bf16_f32 v13, v10, v11
	v_mul_f32_e32 v14, v4, v21
	v_mul_f32_e32 v15, v5, v21
	v_lshl_add_u64 v[4:5], v[72:73], 0, v[56:57]
	v_lshl_add_u64 v[4:5], v[4:5], 0, v[88:89]
	v_lshl_add_u64 v[4:5], v[4:5], 0, v[44:45]
	global_store_dwordx2 v[4:5], v[12:13], off
	v_mul_f32_e32 v4, v14, v168
	v_mul_f32_e32 v5, v15, v169
	v_mul_f32_e32 v8, v16, v170
	v_mul_f32_e32 v9, v17, v171
	v_cvt_pk_bf16_f32 v4, v4, v5
	v_cvt_pk_bf16_f32 v5, v8, v9
	global_store_dwordx2 v[6:7], v[4:5], off
	s_andn2_b64 exec, exec, s[12:13]
	s_cbranch_execnz .LBB0_541

; #define p getp()
; template <int MODE>
; __device__ __forceinline__ void rms_rows(KP p, const float* __restrict__ g, int wv) {
;     ...
;   for (int row = blockIdx.x * 8 + wid; row < TOK; row += gridDim.x * 8) {
;     const float* src;
;     if (MODE == 0) src = (row < SEQ) ? p->x_prompt + (long)row * DM : p->x_sample + (long)(row - SEQ) * DM;
;     else src = p->X + (long)row * DM;
;     f32x4 v[8];
; #pragma unroll
;     for (int i = 0; i < 8; ++i) v[i] = *reinterpret_cast<const f32x4*>(src + (i * 64 + lane) * 4);
;     float ss = 0.f;
; #pragma unroll
;     for (int i = 0; i < 8; ++i) ss += v[i][0] * v[i][0] + v[i][1] * v[i][1] + v[i][2] * v[i][2] + v[i][3] * v[i][3];
;     ss = wave_sum(ss);
;     const float rstd = rsqrtf(ss * (1.f / DM) + 1e-6f);
.LBB0_675:
	v_ashrrev_i32_e32 v21, 31, v20
	v_lshlrev_b64 v[4:5], 13, v[20:21]
	v_lshl_add_u64 v[4:5], s[10:11], 0, v[4:5]
	v_mov_b32_e32 v39, v23
	v_mov_b32_e32 v41, v23
	v_mov_b32_e32 v43, v23
	v_mov_b32_e32 v45, v23
	v_lshl_add_u64 v[88:89], v[4:5], 0, v[22:23]
	v_lshl_add_u64 v[90:91], v[4:5], 0, v[38:39]
	v_lshl_add_u64 v[92:93], v[4:5], 0, v[40:41]
	v_lshl_add_u64 v[94:95], v[4:5], 0, v[42:43]
	v_lshl_add_u64 v[96:97], v[4:5], 0, v[44:45]
	global_load_dwordx4 v[72:75], v[88:89], off nt
	global_load_dwordx4 v[76:79], v[88:89], off offset:1024 nt
	global_load_dwordx4 v[80:83], v[88:89], off offset:2048 nt
	global_load_dwordx4 v[84:87], v[88:89], off offset:3072 nt
	global_load_dwordx4 v[16:19], v[90:91], off nt
	global_load_dwordx4 v[12:15], v[92:93], off nt
	global_load_dwordx4 v[8:11], v[94:95], off nt
	global_load_dwordx4 v[4:7], v[96:97], off nt
	v_mov_b32_e32 v47, v23
	v_mov_b32_e32 v49, v23
	v_mov_b32_e32 v51, v23
	v_mov_b32_e32 v53, v23
	v_mov_b32_e32 v55, v23
	v_mov_b32_e32 v57, v23
	v_mov_b32_e32 v59, v23
	v_mov_b32_e32 v61, v23
	v_mov_b32_e32 v63, v23
	s_waitcnt vmcnt(7)
	v_mul_f32_e32 v21, v73, v73
	s_waitcnt vmcnt(6)
	v_mul_f32_e32 v39, v77, v77
	s_waitcnt vmcnt(5)
	v_mul_f32_e32 v41, v81, v81
	v_fmac_f32_e32 v21, v72, v72
	v_fmac_f32_e32 v39, v76, v76
	s_waitcnt vmcnt(4)
	v_mul_f32_e32 v43, v85, v85
	s_waitcnt vmcnt(3)
	v_mov_b32_e32 v90, v17
	s_waitcnt vmcnt(2)
	v_mov_b32_e32 v91, v13
	v_fmac_f32_e32 v41, v80, v80
	v_fmac_f32_e32 v21, v74, v74
	v_fmac_f32_e32 v39, v78, v78
	v_mov_b32_e32 v88, v16
	v_mov_b32_e32 v89, v12
	v_fmac_f32_e32 v43, v84, v84
	v_pk_mul_f32 v[90:91], v[90:91], v[90:91]
	v_fmac_f32_e32 v41, v82, v82
	v_fmac_f32_e32 v21, v75, v75
	v_fmac_f32_e32 v39, v79, v79
	v_mov_b32_e32 v92, v18
	v_mov_b32_e32 v93, v14
	s_waitcnt vmcnt(1)
	v_mov_b32_e32 v98, v9
	s_waitcnt vmcnt(0)
	v_mov_b32_e32 v99, v5
	v_fmac_f32_e32 v43, v86, v86
	v_pk_fma_f32 v[88:89], v[88:89], v[88:89], v[90:91]
	v_fmac_f32_e32 v41, v83, v83
	v_add_f32_e32 v21, v21, v39
	v_mov_b32_e32 v94, v19
	v_mov_b32_e32 v95, v15
	v_mov_b32_e32 v96, v8
	v_mov_b32_e32 v97, v4
	v_pk_mul_f32 v[98:99], v[98:99], v[98:99]
	v_fmac_f32_e32 v43, v87, v87
	v_pk_fma_f32 v[88:89], v[92:93], v[92:93], v[88:89]
	v_add_f32_e32 v21, v21, v41
	v_mov_b32_e32 v100, v10
	v_mov_b32_e32 v101, v6
	v_pk_fma_f32 v[90:91], v[96:97], v[96:97], v[98:99]
	v_pk_fma_f32 v[88:89], v[94:95], v[94:95], v[88:89]
	v_add_f32_e32 v21, v21, v43
	v_mov_b32_e32 v102, v11
	v_mov_b32_e32 v103, v7
	v_pk_fma_f32 v[90:91], v[100:101], v[100:101], v[90:91]
	v_add_f32_e32 v21, v21, v88
	v_pk_fma_f32 v[90:91], v[102:103], v[102:103], v[90:91]
	v_add_f32_e32 v21, v21, v89
	v_add_f32_e32 v21, v21, v90
	v_add_f32_e32 v21, v21, v91
	ds_bpermute_b32 v39, v64, v21
	v_ashrrev_i32_e32 v90, 8, v20
	v_ashrrev_i32_e32 v91, 31, v90
	v_lshlrev_b64 v[90:91], 20, v[90:91]
	v_mov_b32_e32 v93, v23
	s_waitcnt lgkmcnt(0)
	v_add_f32_e32 v21, v21, v39
	ds_bpermute_b32 v39, v65, v21
	v_add_u32_e32 v20, s0, v20
	s_waitcnt lgkmcnt(0)
	v_add_f32_e32 v21, v21, v39
	ds_bpermute_b32 v39, v66, v21
	s_waitcnt lgkmcnt(0)
	v_add_f32_e32 v21, v21, v39
	ds_bpermute_b32 v39, v67, v21
	s_waitcnt lgkmcnt(0)
	v_add_f32_e32 v21, v21, v39
	ds_bpermute_b32 v39, v68, v21
	s_waitcnt lgkmcnt(0)
	v_add_f32_e32 v21, v21, v39
	ds_bpermute_b32 v39, v69, v21
	s_waitcnt lgkmcnt(0)
	v_add_f32_e32 v21, v21, v39
	v_fmamk_f32 v21, v21, 0x3a000000, v71
	v_mul_f32_e32 v39, 0x4b800000, v21
	v_cmp_gt_f32_e32 vcc, s1, v21
	s_nop 1
	v_cndmask_b32_e32 v21, v21, v39, vcc
	v_rsq_f32_e32 v21, v21
	s_nop 0
	v_mul_f32_e32 v39, 0x45800000, v21
	v_cndmask_b32_e32 v21, v21, v39, vcc
	v_mul_f32_e32 v39, v72, v21
	v_mul_f32_e32 v41, v73, v21
	v_mul_f32_e32 v43, v74, v21
	v_mul_f32_e32 v45, v75, v21
	v_mul_f32_e32 v39, v0, v39
	v_mul_f32_e32 v41, v1, v41
	v_mul_f32_e32 v43, v2, v43
	v_mul_f32_e32 v45, v3, v45
	v_cvt_pk_bf16_f32 v88, v39, v41
	v_cvt_pk_bf16_f32 v89, v43, v45
	s_load_dwordx2 s[16:17], s[6:7], 0xa8
	v_and_b32_e32 v39, 0x3fc0, v70
	v_lshlrev_b32_e32 v92, 1, v39
	v_mul_f32_e32 v39, v76, v21
	v_mul_f32_e32 v41, v77, v21
	s_waitcnt lgkmcnt(0)
; __device__ __forceinline__ long ablk(int row, int col, int nkt) { return ((long)(row >> 8) * nkt + (col >> 6)) * 16384 + (row & 255) * 64 + (col & 63); }
; #define p getp()
; template <int MODE>
; __device__ __forceinline__ void rms_rows(KP p, const float* __restrict__ g, int wv) {
;     ...
; #pragma unroll
;     for (int i = 0; i < 8; ++i) {
;       const int c = (i * 64 + lane) * 4;
;       f32x4 gg = *reinterpret_cast<const f32x4*>(g + c);
;       f32x4 y = {v[i][0] * rstd * gg[0], v[i][1] * rstd * gg[1], v[i][2] * rstd * gg[2], v[i][3] * rstd * gg[3]};
;       if (MODE == 2) *reinterpret_cast<f32x4*>(p->X + (long)row * DM + c) = y;
;       else { u32x2 w = {cvtpk(y[0], y[1]), cvtpk(y[2], y[3])}; *reinterpret_cast<u32x2*>(P_H + ablk(row, c, DM / 64)) = w; }
;     }
	v_lshl_add_u64 v[76:77], s[16:17], 0, v[90:91]
	v_lshl_add_u64 v[76:77], v[76:77], 0, s[14:15]
	v_mul_f32_e32 v43, v78, v21
	v_mul_f32_e32 v45, v79, v21
	v_lshl_add_u64 v[78:79], v[76:77], 0, v[46:47]
	v_lshl_add_u64 v[78:79], v[78:79], 0, v[92:93]
	v_lshl_add_u64 v[78:79], v[78:79], 0, v[48:49]
	global_store_dwordx2 v[78:79], v[88:89], off
	v_mul_f32_e32 v18, v18, v21
	v_mul_f32_e32 v19, v19, v21
	v_mul_f32_e32 v14, v14, v21
	v_mul_f32_e32 v15, v15, v21
	v_mul_f32_e32 v10, v10, v21
	v_mul_f32_e32 v11, v11, v21
	v_cmp_lt_i32_e32 vcc, s3, v20
	v_add_u32_e32 v70, s38, v70
	s_or_b64 s[12:13], vcc, s[12:13]
	v_mul_f32_e32 v39, v144, v39
	v_mul_f32_e32 v41, v145, v41
	v_mul_f32_e32 v43, v146, v43
	v_mul_f32_e32 v45, v147, v45
	v_cvt_pk_bf16_f32 v78, v39, v41
	v_cvt_pk_bf16_f32 v79, v43, v45
	v_mul_f32_e32 v39, v80, v21
	v_mul_f32_e32 v41, v81, v21
	v_lshl_add_u64 v[80:81], v[76:77], 0, v[50:51]
	v_lshl_add_u64 v[80:81], v[80:81], 0, v[92:93]
	v_mul_f32_e32 v43, v82, v21
	v_mul_f32_e32 v45, v83, v21
	v_lshl_add_u64 v[80:81], v[80:81], 0, v[48:49]
	global_store_dwordx2 v[80:81], v[78:79], off
	v_lshl_add_u64 v[80:81], v[76:77], 0, v[52:53]
	v_lshl_add_u64 v[80:81], v[80:81], 0, v[92:93]
	v_lshl_add_u64 v[80:81], v[80:81], 0, v[48:49]
	v_mul_f32_e32 v39, v148, v39
	v_mul_f32_e32 v41, v149, v41
	v_mul_f32_e32 v43, v150, v43
	v_mul_f32_e32 v45, v151, v45
	v_cvt_pk_bf16_f32 v78, v39, v41
	v_cvt_pk_bf16_f32 v79, v43, v45
	v_mul_f32_e32 v39, v84, v21
	v_mul_f32_e32 v41, v85, v21
	v_mul_f32_e32 v43, v86, v21
	v_mul_f32_e32 v45, v87, v21
	global_store_dwordx2 v[80:81], v[78:79], off
	v_mul_f32_e32 v39, v39, v152
	v_mul_f32_e32 v41, v41, v153
	v_mul_f32_e32 v43, v43, v154
	v_mul_f32_e32 v45, v45, v155
	v_cvt_pk_bf16_f32 v78, v39, v41
	v_cvt_pk_bf16_f32 v79, v43, v45
	v_mul_f32_e32 v39, v16, v21
	v_mul_f32_e32 v41, v17, v21
	v_lshl_add_u64 v[16:17], v[76:77], 0, v[54:55]
	v_lshl_add_u64 v[16:17], v[16:17], 0, v[92:93]
	v_lshl_add_u64 v[16:17], v[16:17], 0, v[48:49]
	global_store_dwordx2 v[16:17], v[78:79], off
	v_mul_f32_e32 v16, v39, v156
	v_mul_f32_e32 v17, v41, v157
	v_mul_f32_e32 v18, v18, v158
	v_mul_f32_e32 v19, v19, v159
	v_cvt_pk_bf16_f32 v72, v16, v17
	v_cvt_pk_bf16_f32 v73, v18, v19
	v_mul_f32_e32 v39, v12, v21
	v_mul_f32_e32 v41, v13, v21
	v_lshl_add_u64 v[12:13], v[76:77], 0, v[56:57]
	v_lshl_add_u64 v[12:13], v[12:13], 0, v[92:93]
	v_lshl_add_u64 v[12:13], v[12:13], 0, v[48:49]
	global_store_dwordx2 v[12:13], v[72:73], off
	v_mul_f32_e32 v12, v39, v160
	v_mul_f32_e32 v13, v41, v161
	v_mul_f32_e32 v14, v14, v162
	v_mul_f32_e32 v15, v15, v163
	v_cvt_pk_bf16_f32 v16, v12, v13
	v_cvt_pk_bf16_f32 v17, v14, v15
	v_mul_f32_e32 v18, v8, v21
	v_mul_f32_e32 v19, v9, v21
	v_lshl_add_u64 v[8:9], v[76:77], 0, v[58:59]
	v_lshl_add_u64 v[8:9], v[8:9], 0, v[92:93]
	v_lshl_add_u64 v[8:9], v[8:9], 0, v[48:49]
	global_store_dwordx2 v[8:9], v[16:17], off
	v_mul_f32_e32 v16, v6, v21
	v_mul_f32_e32 v17, v7, v21
	v_lshl_add_u64 v[6:7], v[76:77], 0, v[62:63]
	v_lshl_add_u64 v[6:7], v[6:7], 0, v[92:93]
	v_lshl_add_u64 v[6:7], v[6:7], 0, v[48:49]
	v_mul_f32_e32 v8, v18, v164
	v_mul_f32_e32 v9, v19, v165
	v_mul_f32_e32 v10, v10, v166
	v_mul_f32_e32 v11, v11, v167
	v_cvt_pk_bf16_f32 v12, v8, v9
	v_cvt_pk_bf16_f32 v13, v10, v11
	v_mul_f32_e32 v14, v4, v21
	v_mul_f32_e32 v15, v5, v21
	v_lshl_add_u64 v[4:5], v[76:77], 0, v[60:61]
	v_lshl_add_u64 v[4:5], v[4:5], 0, v[92:93]
	v_lshl_add_u64 v[4:5], v[4:5], 0, v[48:49]
	global_store_dwordx2 v[4:5], v[12:13], off
	v_mul_f32_e32 v4, v14, v168
	v_mul_f32_e32 v5, v15, v169
	v_mul_f32_e32 v8, v16, v170
	v_mul_f32_e32 v9, v17, v171
	v_cvt_pk_bf16_f32 v4, v4, v5
	v_cvt_pk_bf16_f32 v5, v8, v9
	global_store_dwordx2 v[6:7], v[4:5], off
	s_andn2_b64 exec, exec, s[12:13]
	s_cbranch_execnz .LBB0_675

; __device__ __forceinline__ unsigned short f2bf(float x) { return (unsigned short)(cvtpk(x, x) & 0xffffu); }
; #define p getp()
; __device__ __forceinline__ void phase_mla_norm(KP p, int wv) {
;     ...
;   for (int t = blockIdx.x * 8 + wid; t < TOK; t += gridDim.x * 8) {
;     const float* d = dn + (long)t * NDN;
;     float a[6], c[8];
; #pragma unroll
;     for (int i = 0; i < 6; ++i) a[i] = d[i * 64 + lane];
; #pragma unroll
;     for (int i = 0; i < 8; ++i) c[i] = d[384 + i * 64 + lane];
;     const float kr = d[896 + lane];
;     float sa = 0.f, sc = 0.f;
; #pragma unroll
;     for (int i = 0; i < 6; ++i) sa += a[i] * a[i];
; #pragma unroll
;     for (int i = 0; i < 8; ++i) sc += c[i] * c[i];
;     sa = wave_sum(sa); sc = wave_sum(sc);
;     const float ra = rsqrtf(sa * (1.f / RQ) + 1e-6f), rc = rsqrtf(sc * (1.f / RKV) + 1e-6f);
; #pragma unroll
;     for (int i = 0; i < 6; ++i) cq[(long)t * RQ + i * 64 + lane] = f2bf(a[i] * ra * p->mla_g_q[i * 64 + lane]);
; #pragma unroll
;     for (int i = 0; i < 8; ++i) ckv[(long)t * RKV + i * 64 + lane] = f2bf(c[i] * rc * p->mla_g_kv[i * 64 + lane]);
;     const float other = __shfl_xor(kr, 32);
;     const float cs = P_ropeC[(t & (SEQ - 1)) * 32 + (lane & 31)], sn = P_ropeS[(t & (SEQ - 1)) * 32 + (lane & 31)];
;     const float out = (lane < 32) ? kr * cs - other * sn : other * sn + kr * cs;
;     const unsigned char ob = (unsigned char)(__builtin_amdgcn_cvt_pk_fp8_f32(out, out, 0, false) & 0xff);
; #pragma unroll
;     for (int h = 0; h < 16; ++h) K8[(long)t * NUQ + h * 192 + 128 + lane] = ob;
.LBB0_762:
	v_ashrrev_i32_e32 v1, 31, v0
	v_lshlrev_b64 v[14:15], 12, v[0:1]
	v_lshl_add_u64 v[24:25], v[10:11], 0, v[14:15]
	global_load_dword v48, v[24:25], off nt
	global_load_dword v27, v[24:25], off offset:256 nt
	global_load_dword v28, v[24:25], off offset:512 nt
	global_load_dword v29, v[24:25], off offset:768 nt
	global_load_dword v30, v[24:25], off offset:1024 nt
	global_load_dword v31, v[24:25], off offset:1280 nt
	global_load_dword v32, v[24:25], off offset:1536 nt
	global_load_dword v49, v[24:25], off offset:1792 nt
	global_load_dword v33, v[24:25], off offset:2048 nt
	global_load_dword v26, v[24:25], off offset:2304 nt
	global_load_dword v34, v[24:25], off offset:2560 nt
	global_load_dword v35, v[24:25], off offset:2816 nt
	global_load_dword v14, v[24:25], off offset:3072 nt
	global_load_dword v15, v[24:25], off offset:3328 nt
	global_load_dword v50, v[8:9], off
	global_load_dword v51, v[24:25], off offset:3584 nt
	s_waitcnt vmcnt(15)
	v_mul_f32_e32 v45, v48, v48
	s_waitcnt vmcnt(12)
	v_pk_mul_f32 v[24:25], v[28:29], v[28:29]
	s_nop 0
	v_mov_b32_e32 v47, v24
	s_waitcnt vmcnt(10)
	v_pk_mul_f32 v[36:37], v[30:31], v[30:31]
	s_waitcnt vmcnt(7)
	v_pk_mul_f32 v[38:39], v[32:33], v[32:33]
	s_nop 0
	v_fma_f32 v38, v49, v49, v38
	v_add_f32_e32 v44, v38, v39
	s_waitcnt vmcnt(4)
	v_pk_mul_f32 v[40:41], v[34:35], v[34:35]
	v_pk_fma_f32 v[38:39], v[26:27], v[26:27], v[44:45]
	v_mov_b32_e32 v46, v40
	s_waitcnt vmcnt(2)
	v_pk_mul_f32 v[42:43], v[14:15], v[14:15]
	v_mov_b32_e32 v24, v41
	v_pk_add_f32 v[38:39], v[38:39], v[46:47]
	v_mov_b32_e32 v40, v42
	v_mov_b32_e32 v41, v36
	v_pk_add_f32 v[24:25], v[38:39], v[24:25]
	v_mov_b32_e32 v36, v43
	v_pk_add_f32 v[24:25], v[24:25], v[40:41]
	s_nop 0
	v_pk_add_f32 v[24:25], v[24:25], v[36:37]
	ds_bpermute_b32 v37, v13, v25
	ds_bpermute_b32 v36, v13, v24
	s_waitcnt lgkmcnt(0)
	v_pk_add_f32 v[24:25], v[24:25], v[36:37]
	ds_bpermute_b32 v37, v16, v25
	ds_bpermute_b32 v36, v16, v24
	s_waitcnt lgkmcnt(0)
	v_pk_add_f32 v[24:25], v[24:25], v[36:37]
	ds_bpermute_b32 v37, v17, v25
	ds_bpermute_b32 v36, v17, v24
	s_waitcnt lgkmcnt(0)
	v_pk_add_f32 v[24:25], v[24:25], v[36:37]
	ds_bpermute_b32 v37, v18, v25
	ds_bpermute_b32 v36, v18, v24
	s_waitcnt lgkmcnt(0)
	v_pk_add_f32 v[24:25], v[24:25], v[36:37]
	ds_bpermute_b32 v37, v19, v25
	ds_bpermute_b32 v36, v19, v24
	s_waitcnt lgkmcnt(0)
	v_pk_add_f32 v[24:25], v[24:25], v[36:37]
	ds_bpermute_b32 v37, v20, v25
	ds_bpermute_b32 v36, v20, v24
	s_waitcnt lgkmcnt(0)
	v_pk_add_f32 v[24:25], v[24:25], v[36:37]
	s_nop 0
	v_pk_fma_f32 v[24:25], v[24:25], s[18:19], v[12:13] op_sel_hi:[1,1,0]
	s_nop 0
	v_mul_f32_e32 v36, 0x4b800000, v25
	v_cmp_gt_f32_e64 s[6:7], s3, v25
	s_nop 1
	v_cndmask_b32_e64 v25, v25, v36, s[6:7]
	v_rsq_f32_e32 v25, v25
	s_nop 0
	v_mul_f32_e32 v36, 0x45800000, v25
	v_cndmask_b32_e64 v25, v25, v36, s[6:7]
	v_mul_f32_e32 v36, v48, v25
	s_waitcnt vmcnt(0)
	v_mul_f32_e32 v36, v50, v36
	v_cvt_pk_bf16_f32 v38, v36, v36
	v_mul_f32_e32 v27, v27, v25
	v_mad_i64_i32 v[36:37], s[6:7], v0, s20, v[2:3]
	global_store_short v[36:37], v38, off
	v_mul_f32_e32 v28, v28, v25
	v_mul_f32_e32 v29, v29, v25
	v_cmp_gt_f32_e64 s[6:7], s3, v24
	v_mul_f32_e32 v27, v27, v144
	v_cvt_pk_bf16_f32 v27, v27, v27
	s_nop 0
	global_store_short v[36:37], v27, off offset:128
	v_mul_f32_e32 v27, v28, v145
	v_cvt_pk_bf16_f32 v27, v27, v27
	s_nop 0
	global_store_short v[36:37], v27, off offset:256
	v_mul_f32_e32 v27, v29, v146
	v_cvt_pk_bf16_f32 v27, v27, v27
	v_mul_f32_e32 v29, v30, v25
	global_store_short v[36:37], v27, off offset:384
	v_mul_f32_e32 v25, v31, v25
	v_mul_f32_e32 v27, v29, v147
	v_cvt_pk_bf16_f32 v27, v27, v27
	v_mul_f32_e32 v25, v25, v148
	global_store_short v[36:37], v27, off offset:512
	v_cvt_pk_bf16_f32 v25, v25, v25
	v_mul_f32_e32 v28, 0x4b800000, v24
	v_cndmask_b32_e64 v24, v24, v28, s[6:7]
	v_rsq_f32_e32 v24, v24
	global_store_short v[36:37], v25, off offset:640
	s_waitcnt lgkmcnt(0)
	v_mul_f32_e32 v28, 0x45800000, v24
	v_cndmask_b32_e64 v28, v24, v28, s[6:7]
	v_mul_f32_e32 v24, v32, v28
	v_mul_f32_e32 v26, v26, v28
	v_mul_f32_e32 v14, v14, v28
	v_mul_f32_e32 v15, v15, v28
	v_mul_f32_e32 v24, v24, v149
	v_cvt_pk_bf16_f32 v27, v24, v24
	v_lshlrev_b64 v[24:25], 10, v[0:1]
	v_mul_f32_e32 v1, v49, v28
	v_lshl_add_u64 v[24:25], v[4:5], 0, v[24:25]
	global_store_short v[24:25], v27, off
	v_mul_f32_e32 v1, v1, v150
	v_cvt_pk_bf16_f32 v1, v1, v1
	v_mul_f32_e32 v29, v33, v28
	global_store_short v[24:25], v1, off offset:128
	v_mul_f32_e32 v1, v29, v151
	v_cvt_pk_bf16_f32 v1, v1, v1
	ds_bpermute_b32 v29, v13, v51
	global_store_short v[24:25], v1, off offset:256
	v_mul_f32_e32 v1, v26, v152
	v_cvt_pk_bf16_f32 v1, v1, v1
	v_mul_f32_e32 v27, v34, v28
	global_store_short v[24:25], v1, off offset:384
	v_mul_f32_e32 v1, v27, v153
	v_cvt_pk_bf16_f32 v1, v1, v1
	v_mul_f32_e32 v27, v35, v28
	global_store_short v[24:25], v1, off offset:512
	v_mul_f32_e32 v1, v27, v154
	v_cvt_pk_bf16_f32 v1, v1, v1
	s_nop 0
	global_store_short v[24:25], v1, off offset:640
	v_mul_f32_e32 v1, v14, v155
	v_cvt_pk_bf16_f32 v1, v1, v1
	v_and_or_b32 v26, v22, s21, v21
	v_lshlrev_b32_e32 v26, 2, v26
	global_store_short v[24:25], v1, off offset:768
	v_add_u32_e32 v22, s1, v22
	v_mul_f32_e32 v1, v15, v156
	v_cvt_pk_bf16_f32 v1, v1, v1
	global_load_dword v27, v26, s[14:15]
	global_load_dword v28, v26, s[12:13]
	v_mov_b32_e32 v26, 0
	global_store_short v[24:25], v1, off offset:896
	v_mad_i64_i32 v[14:15], s[6:7], v0, s22, v[6:7]
	v_add_u32_e32 v0, s0, v0
	v_cmp_lt_i32_e64 s[6:7], s23, v0
	s_or_b64 s[16:17], s[6:7], s[16:17]
	s_waitcnt vmcnt(2) lgkmcnt(0)
	v_mul_f32_e32 v1, v27, v29
	v_cndmask_b32_e64 v1, v1, -v1, vcc
	s_waitcnt vmcnt(1)
	v_fmac_f32_e32 v1, v51, v28
	v_cvt_pk_fp8_f32 v26, v1, v1
	global_store_byte v[14:15], v26, off
	global_store_byte v[14:15], v26, off offset:192
	global_store_byte v[14:15], v26, off offset:384
	global_store_byte v[14:15], v26, off offset:576
	global_store_byte v[14:15], v26, off offset:768
	global_store_byte v[14:15], v26, off offset:960
	global_store_byte v[14:15], v26, off offset:1152
	global_store_byte v[14:15], v26, off offset:1344
	global_store_byte v[14:15], v26, off offset:1536
	global_store_byte v[14:15], v26, off offset:1728
	global_store_byte v[14:15], v26, off offset:1920
	global_store_byte v[14:15], v26, off offset:2112
	global_store_byte v[14:15], v26, off offset:2304
	global_store_byte v[14:15], v26, off offset:2496
	global_store_byte v[14:15], v26, off offset:2688
	global_store_byte v[14:15], v26, off offset:2880
	s_andn2_b64 exec, exec, s[16:17]
	s_cbranch_execnz .LBB0_762
